# grid barrier: acquire-side L1 invalidate issued at arrival (overlaps the wait for the release) instead of after the release
# speedup vs baseline: 1.0054x; 1.0054x over previous
; __device__ __forceinline__ unsigned xb_ld_u(unsigned* p) { return (unsigned)__builtin_amdgcn_readfirstlane((int)__hip_atomic_load(p, RLX_AGENT)); }
; __device__ __forceinline__ unsigned xb_add_u(unsigned* p, unsigned v, int lane) { unsigned r = 0u; if (lane == 0) r = __hip_atomic_fetch_add(p, v, RLX_AGENT); return (unsigned)__builtin_amdgcn_readfirstlane((int)r); }
; #define XB_SPIN_U(cond, bar) do { unsigned _sp = 0; while (cond) { __builtin_amdgcn_s_sleep(1); if (++_sp > XB_SPIN_CAP) { if (lane == 0) atomicAdd(&(bar)[XB_TMO], 1u); break; } } } while (0)
; __device__ __forceinline__ void xcd_barrier(unsigned* bar, volatile __attribute__((address_space(3))) unsigned* st, int wave, int lane) {
;     ...
;         const unsigned old = xb_add_u(&bar[XB_XSUB(x)], 1u, lane), gen = old / nloc;
;         if (old + 1u == (gen + 1u) * nloc) {
;             __builtin_amdgcn_fence(__ATOMIC_RELEASE, "agent");
;             asm volatile("s_waitcnt vmcnt(0)" ::: "memory");
;             const unsigned og = xb_add_u(&bar[XB_TOP], 1u, lane), tg = og / nx;
;             if (og + 1u == (tg + 1u) * nx) (void)xb_add_u(&bar[XB_TOPGEN], 1u, lane);
;             else XB_SPIN_U(xb_ld_u(&bar[XB_TOPGEN]) == tg, bar);
;             __builtin_amdgcn_fence(__ATOMIC_ACQUIRE, "agent");
;             (void)xb_add_u(&bar[XB_XGEN(x)], 1u, lane);
;             asm volatile("s_waitcnt vmcnt(0)" ::: "memory");
;         } else {
;             XB_SPIN_U(xb_ld_u(&bar[XB_XGEN(x)]) == gen, bar);
;             __builtin_amdgcn_fence(__ATOMIC_ACQUIRE, "agent");
.LBB0_86:
	s_or_b64 exec, exec, s[6:7]
	v_cvt_f32_u32_e32 v4, v2
	s_waitcnt vmcnt(0) lgkmcnt(0)
	v_readfirstlane_b32 s2, v3
	v_sub_u32_e32 v3, 0, v2
	s_add_i32 s8, s2, 1
	v_rcp_iflag_f32_e32 v4, v4
	s_nop 0
	v_mul_f32_e32 v4, 0x4f7ffffe, v4
	v_cvt_u32_f32_e32 v4, v4
	v_mul_lo_u32 v3, v3, v4
	v_mul_hi_u32 v3, v4, v3
	v_add_u32_e32 v3, v4, v3
	v_mul_hi_u32 v3, s2, v3
	v_mul_lo_u32 v4, v3, v2
	v_sub_u32_e32 v4, s2, v4
	v_add_u32_e32 v5, 1, v3
	v_cmp_ge_u32_e32 vcc, v4, v2
	s_nop 1
	v_cndmask_b32_e32 v3, v3, v5, vcc
	v_sub_u32_e32 v5, v4, v2
	v_cndmask_b32_e32 v4, v4, v5, vcc
	v_add_u32_e32 v5, 1, v3
	v_cmp_ge_u32_e32 vcc, v4, v2
	s_nop 1
	v_cndmask_b32_e32 v3, v3, v5, vcc
	v_mad_u64_u32 v[4:5], s[6:7], v2, v3, v[2:3]
	v_cmp_ne_u32_e32 vcc, s8, v4
	s_and_saveexec_b64 s[6:7], vcc
	s_xor_b64 s[6:7], exec, s[6:7]
	s_cbranch_execz .LBB0_104
	buffer_inv sc1
	s_add_u32 s14, s1, 0x2400
	s_addc_u32 s15, s0, 0
	s_mov_b32 s2, 0x400001
	s_mov_b64 s[16:17], 0
	s_branch .LBB0_93

; __device__ __forceinline__ unsigned xb_ld_u(unsigned* p) { return (unsigned)__builtin_amdgcn_readfirstlane((int)__hip_atomic_load(p, RLX_AGENT)); }
; __device__ __forceinline__ unsigned xb_add_u(unsigned* p, unsigned v, int lane) { unsigned r = 0u; if (lane == 0) r = __hip_atomic_fetch_add(p, v, RLX_AGENT); return (unsigned)__builtin_amdgcn_readfirstlane((int)r); }
; #define XB_SPIN_U(cond, bar) do { unsigned _sp = 0; while (cond) { __builtin_amdgcn_s_sleep(1); if (++_sp > XB_SPIN_CAP) { if (lane == 0) atomicAdd(&(bar)[XB_TMO], 1u); break; } } } while (0)
; __device__ __forceinline__ void xcd_barrier(unsigned* bar, volatile __attribute__((address_space(3))) unsigned* st, int wave, int lane) {
;     ...
;         const unsigned old = xb_add_u(&bar[XB_XSUB(x)], 1u, lane), gen = old / nloc;
;         if (old + 1u == (gen + 1u) * nloc) {
;             __builtin_amdgcn_fence(__ATOMIC_RELEASE, "agent");
;             asm volatile("s_waitcnt vmcnt(0)" ::: "memory");
;             const unsigned og = xb_add_u(&bar[XB_TOP], 1u, lane), tg = og / nx;
;             if (og + 1u == (tg + 1u) * nx) (void)xb_add_u(&bar[XB_TOPGEN], 1u, lane);
;             else XB_SPIN_U(xb_ld_u(&bar[XB_TOPGEN]) == tg, bar);
.LBB0_103:
	s_or_b64 exec, exec, s[14:15]
	s_waitcnt vmcnt(0) lgkmcnt(0)
	s_nop 0
	s_waitcnt vmcnt(0)
.LBB0_104:
	s_andn2_saveexec_b64 s[14:15], s[6:7]
	s_cbranch_execz .LBB0_133
	buffer_wbl2 sc1
	buffer_inv sc1
	s_waitcnt vmcnt(0)
	v_mov_b32_e32 v2, 0
	s_and_saveexec_b64 s[6:7], s[4:5]
	s_cbranch_execz .LBB0_107
	v_mov_b32_e32 v2, s12
	v_add_co_u32_e32 v2, vcc, 0xe203000, v2
	v_mov_b32_e32 v3, s13
	s_nop 0
	v_addc_co_u32_e32 v3, vcc, 0, v3, vcc
	flat_atomic_add v2, v[2:3], v244 offset:1024 sc0

; __device__ __forceinline__ unsigned xb_ld_u(unsigned* p) { return (unsigned)__builtin_amdgcn_readfirstlane((int)__hip_atomic_load(p, RLX_AGENT)); }
; __device__ __forceinline__ unsigned xb_add_u(unsigned* p, unsigned v, int lane) { unsigned r = 0u; if (lane == 0) r = __hip_atomic_fetch_add(p, v, RLX_AGENT); return (unsigned)__builtin_amdgcn_readfirstlane((int)r); }
; #define XB_SPIN_U(cond, bar) do { unsigned _sp = 0; while (cond) { __builtin_amdgcn_s_sleep(1); if (++_sp > XB_SPIN_CAP) { if (lane == 0) atomicAdd(&(bar)[XB_TMO], 1u); break; } } } while (0)
; __device__ __forceinline__ void xcd_barrier(unsigned* bar, volatile __attribute__((address_space(3))) unsigned* st, int wave, int lane) {
;     ...
;             const unsigned og = xb_add_u(&bar[XB_TOP], 1u, lane), tg = og / nx;
;             if (og + 1u == (tg + 1u) * nx) (void)xb_add_u(&bar[XB_TOPGEN], 1u, lane);
;             else XB_SPIN_U(xb_ld_u(&bar[XB_TOPGEN]) == tg, bar);
;             __builtin_amdgcn_fence(__ATOMIC_ACQUIRE, "agent");
.LBB0_128:
	s_nop 0
	s_andn2_b64 s[20:21], s[20:21], exec
	s_or_b64 exec, exec, s[6:7]
	s_and_saveexec_b64 s[6:7], s[20:21]
	s_cbranch_execz .LBB0_111

; __device__ __forceinline__ unsigned xb_add_u(unsigned* p, unsigned v, int lane) { unsigned r = 0u; if (lane == 0) r = __hip_atomic_fetch_add(p, v, RLX_AGENT); return (unsigned)__builtin_amdgcn_readfirstlane((int)r); }
; __device__ __forceinline__ void xcd_barrier(unsigned* bar, volatile __attribute__((address_space(3))) unsigned* st, int wave, int lane) {
;     ...
;             __builtin_amdgcn_fence(__ATOMIC_ACQUIRE, "agent");
;             (void)xb_add_u(&bar[XB_XGEN(x)], 1u, lane);
;             asm volatile("s_waitcnt vmcnt(0)" ::: "memory");
.LBB0_130:
	s_waitcnt vmcnt(0) lgkmcnt(0)
	s_nop 0
	s_and_b64 exec, exec, s[4:5]
	s_cbranch_execz .LBB0_132
	v_mov_b32_e32 v0, s1
	v_add_co_u32_e32 v0, vcc, 0x2000, v0
	v_mov_b32_e32 v1, s0
	s_nop 0
	v_addc_co_u32_e32 v1, vcc, 0, v1, vcc
	flat_atomic_add v[0:1], v244 offset:1024

; __device__ __forceinline__ unsigned xb_ld_u(unsigned* p) { return (unsigned)__builtin_amdgcn_readfirstlane((int)__hip_atomic_load(p, RLX_AGENT)); }
; __device__ __forceinline__ unsigned xb_add_u(unsigned* p, unsigned v, int lane) { unsigned r = 0u; if (lane == 0) r = __hip_atomic_fetch_add(p, v, RLX_AGENT); return (unsigned)__builtin_amdgcn_readfirstlane((int)r); }
; #define XB_SPIN_U(cond, bar) do { unsigned _sp = 0; while (cond) { __builtin_amdgcn_s_sleep(1); if (++_sp > XB_SPIN_CAP) { if (lane == 0) atomicAdd(&(bar)[XB_TMO], 1u); break; } } } while (0)
; __device__ __forceinline__ void xcd_barrier(unsigned* bar, volatile __attribute__((address_space(3))) unsigned* st, int wave, int lane) {
;     ...
;         const unsigned old = xb_add_u(&bar[XB_XSUB(x)], 1u, lane), gen = old / nloc;
;         if (old + 1u == (gen + 1u) * nloc) {
;             __builtin_amdgcn_fence(__ATOMIC_RELEASE, "agent");
;             asm volatile("s_waitcnt vmcnt(0)" ::: "memory");
;             const unsigned og = xb_add_u(&bar[XB_TOP], 1u, lane), tg = og / nx;
;             if (og + 1u == (tg + 1u) * nx) (void)xb_add_u(&bar[XB_TOPGEN], 1u, lane);
;             else XB_SPIN_U(xb_ld_u(&bar[XB_TOPGEN]) == tg, bar);
;             __builtin_amdgcn_fence(__ATOMIC_ACQUIRE, "agent");
;             (void)xb_add_u(&bar[XB_XGEN(x)], 1u, lane);
;             asm volatile("s_waitcnt vmcnt(0)" ::: "memory");
;         } else {
;             XB_SPIN_U(xb_ld_u(&bar[XB_XGEN(x)]) == gen, bar);
;             __builtin_amdgcn_fence(__ATOMIC_ACQUIRE, "agent");
.LBB0_321:
	s_or_b64 exec, exec, s[6:7]
	v_cvt_f32_u32_e32 v4, v2
	s_waitcnt vmcnt(0) lgkmcnt(0)
	v_readfirstlane_b32 s2, v3
	v_sub_u32_e32 v3, 0, v2
	s_add_i32 s12, s2, 1
	v_rcp_iflag_f32_e32 v4, v4
	s_nop 0
	v_mul_f32_e32 v4, 0x4f7ffffe, v4
	v_cvt_u32_f32_e32 v4, v4
	v_mul_lo_u32 v3, v3, v4
	v_mul_hi_u32 v3, v4, v3
	v_add_u32_e32 v3, v4, v3
	v_mul_hi_u32 v3, s2, v3
	v_mul_lo_u32 v4, v3, v2
	v_sub_u32_e32 v4, s2, v4
	v_add_u32_e32 v5, 1, v3
	v_cmp_ge_u32_e32 vcc, v4, v2
	s_nop 1
	v_cndmask_b32_e32 v3, v3, v5, vcc
	v_sub_u32_e32 v5, v4, v2
	v_cndmask_b32_e32 v4, v4, v5, vcc
	v_add_u32_e32 v5, 1, v3
	v_cmp_ge_u32_e32 vcc, v4, v2
	s_nop 1
	v_cndmask_b32_e32 v3, v3, v5, vcc
	v_mad_u64_u32 v[4:5], s[6:7], v2, v3, v[2:3]
	v_cmp_ne_u32_e32 vcc, s12, v4
	s_and_saveexec_b64 s[6:7], vcc
	s_xor_b64 s[6:7], exec, s[6:7]
	s_cbranch_execz .LBB0_339
	buffer_inv sc1
	s_add_u32 s12, s1, 0x2400
	s_addc_u32 s13, s0, 0
	s_mov_b32 s2, 0x400001
	s_mov_b64 s[14:15], 0
	s_branch .LBB0_328

; __device__ __forceinline__ unsigned xb_ld_u(unsigned* p) { return (unsigned)__builtin_amdgcn_readfirstlane((int)__hip_atomic_load(p, RLX_AGENT)); }
; __device__ __forceinline__ unsigned xb_add_u(unsigned* p, unsigned v, int lane) { unsigned r = 0u; if (lane == 0) r = __hip_atomic_fetch_add(p, v, RLX_AGENT); return (unsigned)__builtin_amdgcn_readfirstlane((int)r); }
; #define XB_SPIN_U(cond, bar) do { unsigned _sp = 0; while (cond) { __builtin_amdgcn_s_sleep(1); if (++_sp > XB_SPIN_CAP) { if (lane == 0) atomicAdd(&(bar)[XB_TMO], 1u); break; } } } while (0)
; __device__ __forceinline__ void xcd_barrier(unsigned* bar, volatile __attribute__((address_space(3))) unsigned* st, int wave, int lane) {
;     ...
;         const unsigned old = xb_add_u(&bar[XB_XSUB(x)], 1u, lane), gen = old / nloc;
;         if (old + 1u == (gen + 1u) * nloc) {
;             __builtin_amdgcn_fence(__ATOMIC_RELEASE, "agent");
;             asm volatile("s_waitcnt vmcnt(0)" ::: "memory");
;             const unsigned og = xb_add_u(&bar[XB_TOP], 1u, lane), tg = og / nx;
;             if (og + 1u == (tg + 1u) * nx) (void)xb_add_u(&bar[XB_TOPGEN], 1u, lane);
;             else XB_SPIN_U(xb_ld_u(&bar[XB_TOPGEN]) == tg, bar);
.LBB0_338:
	s_or_b64 exec, exec, s[12:13]
	s_waitcnt vmcnt(0) lgkmcnt(0)
	s_nop 0
	s_waitcnt vmcnt(0)
.LBB0_339:
	s_andn2_saveexec_b64 s[12:13], s[6:7]
	s_cbranch_execz .LBB0_368
	buffer_wbl2 sc1
	buffer_inv sc1
	s_waitcnt vmcnt(0)
	v_mov_b32_e32 v2, 0
	s_and_saveexec_b64 s[6:7], s[4:5]
	s_cbranch_execz .LBB0_342
	v_mov_b32_e32 v2, s10
	v_add_co_u32_e32 v2, vcc, 0xe203000, v2
	v_mov_b32_e32 v3, s11
	s_nop 0
	v_addc_co_u32_e32 v3, vcc, 0, v3, vcc
	flat_atomic_add v2, v[2:3], v244 offset:1024 sc0

; __device__ __forceinline__ unsigned xb_ld_u(unsigned* p) { return (unsigned)__builtin_amdgcn_readfirstlane((int)__hip_atomic_load(p, RLX_AGENT)); }
; __device__ __forceinline__ unsigned xb_add_u(unsigned* p, unsigned v, int lane) { unsigned r = 0u; if (lane == 0) r = __hip_atomic_fetch_add(p, v, RLX_AGENT); return (unsigned)__builtin_amdgcn_readfirstlane((int)r); }
; #define XB_SPIN_U(cond, bar) do { unsigned _sp = 0; while (cond) { __builtin_amdgcn_s_sleep(1); if (++_sp > XB_SPIN_CAP) { if (lane == 0) atomicAdd(&(bar)[XB_TMO], 1u); break; } } } while (0)
; __device__ __forceinline__ void xcd_barrier(unsigned* bar, volatile __attribute__((address_space(3))) unsigned* st, int wave, int lane) {
;     ...
;             const unsigned og = xb_add_u(&bar[XB_TOP], 1u, lane), tg = og / nx;
;             if (og + 1u == (tg + 1u) * nx) (void)xb_add_u(&bar[XB_TOPGEN], 1u, lane);
;             else XB_SPIN_U(xb_ld_u(&bar[XB_TOPGEN]) == tg, bar);
;             __builtin_amdgcn_fence(__ATOMIC_ACQUIRE, "agent");
.LBB0_363:
	s_nop 0
	s_andn2_b64 s[18:19], s[18:19], exec
	s_or_b64 exec, exec, s[6:7]
	s_and_saveexec_b64 s[6:7], s[18:19]
	s_cbranch_execz .LBB0_346

; __device__ __forceinline__ unsigned xb_ld_u(unsigned* p) { return (unsigned)__builtin_amdgcn_readfirstlane((int)__hip_atomic_load(p, RLX_AGENT)); }
; __device__ __forceinline__ unsigned xb_add_u(unsigned* p, unsigned v, int lane) { unsigned r = 0u; if (lane == 0) r = __hip_atomic_fetch_add(p, v, RLX_AGENT); return (unsigned)__builtin_amdgcn_readfirstlane((int)r); }
; #define XB_SPIN_U(cond, bar) do { unsigned _sp = 0; while (cond) { __builtin_amdgcn_s_sleep(1); if (++_sp > XB_SPIN_CAP) { if (lane == 0) atomicAdd(&(bar)[XB_TMO], 1u); break; } } } while (0)
; __device__ __forceinline__ void xcd_barrier(unsigned* bar, volatile __attribute__((address_space(3))) unsigned* st, int wave, int lane) {
;     ...
;         const unsigned old = xb_add_u(&bar[XB_XSUB(x)], 1u, lane), gen = old / nloc;
;         if (old + 1u == (gen + 1u) * nloc) {
;             __builtin_amdgcn_fence(__ATOMIC_RELEASE, "agent");
;             asm volatile("s_waitcnt vmcnt(0)" ::: "memory");
;             const unsigned og = xb_add_u(&bar[XB_TOP], 1u, lane), tg = og / nx;
;             if (og + 1u == (tg + 1u) * nx) (void)xb_add_u(&bar[XB_TOPGEN], 1u, lane);
;             else XB_SPIN_U(xb_ld_u(&bar[XB_TOPGEN]) == tg, bar);
.LBB0_1381:
	buffer_wbl2 sc1
	buffer_inv sc1
	s_waitcnt vmcnt(0)
	v_mov_b32_e32 v2, 0
	s_and_saveexec_b64 s[6:7], s[4:5]
	s_cbranch_execz .LBB0_1383
	v_mov_b32_e32 v2, s10
	v_add_co_u32_e32 v2, vcc, 0xe203000, v2
	v_mov_b32_e32 v3, s11
	s_nop 0
	v_addc_co_u32_e32 v3, vcc, 0, v3, vcc
	flat_atomic_add v2, v[2:3], v244 offset:1024 sc0

; __device__ __forceinline__ unsigned xb_add_u(unsigned* p, unsigned v, int lane) { unsigned r = 0u; if (lane == 0) r = __hip_atomic_fetch_add(p, v, RLX_AGENT); return (unsigned)__builtin_amdgcn_readfirstlane((int)r); }
; __device__ __forceinline__ void xcd_barrier(unsigned* bar, volatile __attribute__((address_space(3))) unsigned* st, int wave, int lane) {
;     ...
;             __builtin_amdgcn_fence(__ATOMIC_ACQUIRE, "agent");
;             (void)xb_add_u(&bar[XB_XGEN(x)], 1u, lane);
;             asm volatile("s_waitcnt vmcnt(0)" ::: "memory");
.LBB0_1406:
	s_waitcnt vmcnt(0) lgkmcnt(0)
	s_nop 0
	s_and_b64 exec, exec, s[4:5]
	s_cbranch_execnz .LBB0_1407
	s_getpc_b64 s[98:99]
